# combination: all 8 DMA pieces of waves 4-7 in VALU-free QK gaps, and waves 0-3 fill their long nop with two V reads
# baseline (speedup 1.0000x reference)
; __device__ __forceinline__ void attn_unit(LAS unsigned char* L, bf16_t* QKV, size_t rowbase, int S, int h, int qb, float lam, const float* subln, unsigned* kmax) {
;     ...
;     for (int t = 0; t < NT; t += 4) { TILE(t, 0); TILE(t + 1, 1); TILE(t + 2, 2); TILE(t + 3, 3); }
.LBB0_927:
	s_add_i32 s69, s68, -3
	v_mfma_f32_32x32x16_bf16 v[96:111], v[132:135], v[116:119], v[64:79]
	v_mfma_f32_32x32x16_bf16 v[96:111], v[140:143], v[120:123], v[96:111]
	s_waitcnt lgkmcnt(10)
	v_mfma_f32_32x32x16_bf16 v[96:111], v[148:151], v[124:127], v[96:111]
	ds_read_b64_tr_b16 v[132:133], v176 offset:4096
	ds_read_b64_tr_b16 v[134:135], v177 offset:6144
	s_waitcnt lgkmcnt(10)
	v_mfma_f32_32x32x16_bf16 v[96:111], v[80:83], v[112:115], v[96:111]
	ds_read_b64_tr_b16 v[140:141], v183 offset:4096
	ds_read_b64_tr_b16 v[142:143], v184 offset:6144
	v_mfma_f32_32x32x16_bf16 v[80:95], v[128:131], v[112:115], v[64:79]
	ds_read_b64_tr_b16 v[128:129], v174 offset:4096
	ds_read_b64_tr_b16 v[130:131], v175 offset:6144
	v_mfma_f32_32x32x16_bf16 v[80:95], v[136:139], v[116:119], v[80:95]
	ds_read_b64_tr_b16 v[136:137], v178 offset:4096
	s_waitcnt lgkmcnt(12)
	ds_read_b64_tr_b16 v[138:139], v179 offset:6144
	s_nop 2
	v_mfma_f32_32x32x16_bf16 v[80:95], v[144:147], v[120:123], v[80:95]
	v_exp_f32_e32 v96, v96
	v_exp_f32_e32 v97, v97
	v_exp_f32_e32 v98, v98
	v_mfma_f32_32x32x16_bf16 v[80:95], v[152:155], v[124:127], v[80:95]
	v_exp_f32_e32 v99, v99
	v_exp_f32_e32 v100, v100
	v_exp_f32_e32 v101, v101
	v_exp_f32_e32 v102, v102
	v_exp_f32_e32 v103, v103
	v_cvt_pk_bf16_f32 v208, v96, v97
	v_cvt_pk_bf16_f32 v209, v98, v99
	v_cvt_pk_bf16_f32 v210, v100, v101
	v_cvt_pk_bf16_f32 v211, v102, v103
	v_exp_f32_e32 v104, v104
	v_exp_f32_e32 v105, v105
	s_waitcnt lgkmcnt(8)
	v_mfma_f32_32x32x16_bf16 v[48:63], v[224:227], v[208:211], v[48:63]
	v_exp_f32_e32 v106, v106
	v_exp_f32_e32 v107, v107
	v_exp_f32_e32 v108, v108
	v_mfma_f32_32x32x16_bf16 v[32:47], v[228:231], v[208:211], v[32:47]
	v_exp_f32_e32 v109, v109
	v_exp_f32_e32 v110, v110
	v_exp_f32_e32 v111, v111
	ds_read_b64_tr_b16 v[144:145], v174 offset:8192
	ds_read_b64_tr_b16 v[146:147], v175 offset:10240
	v_mfma_f32_32x32x16_bf16 v[16:31], v[232:235], v[208:211], v[16:31]
	v_cvt_pk_bf16_f32 v212, v104, v105
	v_cvt_pk_bf16_f32 v213, v106, v107
	v_cvt_pk_bf16_f32 v214, v108, v109
	v_cvt_pk_bf16_f32 v215, v110, v111
	v_add_f32_e32 v187, v96, v187
	v_add_f32_e32 v192, v97, v192
	ds_read_b64_tr_b16 v[148:149], v176 offset:8192
	ds_read_b64_tr_b16 v[150:151], v177 offset:10240
	v_mfma_f32_32x32x16_bf16 v[0:15], v[236:239], v[208:211], v[0:15]
	v_add_f32_e32 v193, v98, v193
	v_add_f32_e32 v194, v99, v194
	v_add_f32_e32 v187, v100, v187
	v_add_f32_e32 v192, v101, v192
	v_add_f32_e32 v193, v102, v193
	v_add_f32_e32 v194, v103, v194
	ds_read_b64_tr_b16 v[152:153], v178 offset:8192
	ds_read_b64_tr_b16 v[154:155], v179 offset:10240
	s_waitcnt lgkmcnt(6)
	v_mfma_f32_32x32x16_bf16 v[48:63], v[128:131], v[212:215], v[48:63]
	v_exp_f32_e32 v80, v80
	v_exp_f32_e32 v81, v81
	v_exp_f32_e32 v82, v82
	ds_read_b64_tr_b16 v[240:241], v183 offset:8192
	ds_read_b64_tr_b16 v[242:243], v184 offset:10240
	ds_read_b128 v[128:131], v188 offset:24576
	v_mfma_f32_32x32x16_bf16 v[32:47], v[132:135], v[212:215], v[32:47]
	v_exp_f32_e32 v83, v83
	v_exp_f32_e32 v84, v84
	v_exp_f32_e32 v85, v85
	ds_read_b64_tr_b16 v[196:197], v174 offset:12288
	ds_read_b64_tr_b16 v[198:199], v175 offset:14336
	ds_read_b128 v[132:135], v189 offset:16384
	v_mfma_f32_32x32x16_bf16 v[16:31], v[136:139], v[212:215], v[16:31]
	v_exp_f32_e32 v86, v86
	v_exp_f32_e32 v87, v87
	v_cvt_pk_bf16_f32 v216, v80, v81
	v_cvt_pk_bf16_f32 v217, v82, v83
	ds_read_b64_tr_b16 v[200:201], v176 offset:12288
	ds_read_b64_tr_b16 v[202:203], v177 offset:14336
	ds_read_b128 v[136:139], v189 offset:24576
	v_mfma_f32_32x32x16_bf16 v[0:15], v[140:143], v[212:215], v[0:15]
	v_cvt_pk_bf16_f32 v218, v84, v85
	v_cvt_pk_bf16_f32 v219, v86, v87
	v_add_f32_e32 v187, v104, v187
	v_add_f32_e32 v192, v105, v192
	v_add_f32_e32 v193, v106, v193
	v_add_f32_e32 v194, v107, v194
	s_waitcnt lgkmcnt(12)
	ds_read_b64_tr_b16 v[204:205], v178 offset:12288
	ds_read_b64_tr_b16 v[206:207], v179 offset:14336
	ds_read_b128 v[140:143], v190 offset:16384
	s_waitcnt lgkmcnt(10)
	v_mfma_f32_32x32x16_bf16 v[48:63], v[144:147], v[216:219], v[48:63]
	v_exp_f32_e32 v88, v88
	v_exp_f32_e32 v89, v89
	v_exp_f32_e32 v90, v90
	ds_read_b64_tr_b16 v[246:247], v183 offset:12288
	ds_read_b64_tr_b16 v[248:249], v184 offset:14336
	ds_read_b128 v[144:147], v190 offset:24576
	v_mfma_f32_32x32x16_bf16 v[32:47], v[148:151], v[216:219], v[32:47]
	v_exp_f32_e32 v91, v91
	v_exp_f32_e32 v92, v92
	v_exp_f32_e32 v93, v93
	ds_read_b128 v[148:151], v191 offset:16384
	v_mfma_f32_32x32x16_bf16 v[16:31], v[152:155], v[216:219], v[16:31]
	v_exp_f32_e32 v94, v94
	v_exp_f32_e32 v95, v95
	v_cvt_pk_bf16_f32 v220, v88, v89
	v_cvt_pk_bf16_f32 v221, v90, v91
	ds_read_b128 v[152:155], v191 offset:24576
	v_mfma_f32_32x32x16_bf16 v[0:15], v[240:243], v[216:219], v[0:15]
	v_cvt_pk_bf16_f32 v222, v92, v93
	v_cvt_pk_bf16_f32 v223, v94, v95
	v_add_f32_e32 v187, v80, v187
	v_add_f32_e32 v192, v81, v192
	v_add_f32_e32 v193, v82, v193
	v_add_f32_e32 v194, v83, v194
	s_waitcnt lgkmcnt(3)
	v_mfma_f32_32x32x16_bf16 v[48:63], v[196:199], v[220:223], v[48:63]
	v_add_f32_e32 v187, v108, v187
	v_add_f32_e32 v192, v109, v192
	v_add_f32_e32 v193, v110, v193
	v_add_f32_e32 v194, v111, v194
	v_add_f32_e32 v187, v84, v187
	v_add_f32_e32 v192, v85, v192
	ds_read_b128 v[80:83], v188 offset:16384
	ds_read_b64_tr_b16 v[224:225], v174 offset:16384
	ds_read_b64_tr_b16 v[226:227], v175 offset:18432
	v_mfma_f32_32x32x16_bf16 v[32:47], v[200:203], v[220:223], v[32:47]
	v_add_f32_e32 v193, v86, v193
	v_add_f32_e32 v194, v87, v194
	v_add_f32_e32 v187, v88, v187
	v_add_f32_e32 v192, v89, v192
	v_add_f32_e32 v193, v90, v193
	v_add_f32_e32 v194, v91, v194
	ds_read_b64_tr_b16 v[228:229], v176 offset:16384
	ds_read_b64_tr_b16 v[230:231], v177 offset:18432
	v_mfma_f32_32x32x16_bf16 v[16:31], v[204:207], v[220:223], v[16:31]
	v_add_f32_e32 v187, v92, v187
	v_add_f32_e32 v192, v93, v192
	v_add_f32_e32 v193, v94, v193
	v_add_f32_e32 v194, v95, v194
	ds_read_b64_tr_b16 v[232:233], v178 offset:16384
	ds_read_b64_tr_b16 v[234:235], v179 offset:18432
	v_mfma_f32_32x32x16_bf16 v[0:15], v[246:249], v[220:223], v[0:15]
	ds_read_b64_tr_b16 v[236:237], v183 offset:16384
	ds_read_b64_tr_b16 v[238:239], v184 offset:18432
	s_barrier
	v_mfma_f32_32x32x16_bf16 v[96:111], v[132:135], v[116:119], v[64:79]
	v_mfma_f32_32x32x16_bf16 v[96:111], v[140:143], v[120:123], v[96:111]
	s_waitcnt lgkmcnt(10)
	v_mfma_f32_32x32x16_bf16 v[96:111], v[148:151], v[124:127], v[96:111]
	ds_read_b64_tr_b16 v[132:133], v176 offset:20480
	ds_read_b64_tr_b16 v[134:135], v177 offset:22528
	s_waitcnt lgkmcnt(10)
	v_mfma_f32_32x32x16_bf16 v[96:111], v[80:83], v[112:115], v[96:111]
	ds_read_b64_tr_b16 v[140:141], v183 offset:20480
	ds_read_b64_tr_b16 v[142:143], v184 offset:22528
	v_mfma_f32_32x32x16_bf16 v[80:95], v[128:131], v[112:115], v[64:79]
	ds_read_b64_tr_b16 v[128:129], v174 offset:20480
	ds_read_b64_tr_b16 v[130:131], v175 offset:22528
	v_mfma_f32_32x32x16_bf16 v[80:95], v[136:139], v[116:119], v[80:95]
	ds_read_b64_tr_b16 v[136:137], v178 offset:20480
	s_waitcnt lgkmcnt(12)
	ds_read_b64_tr_b16 v[138:139], v179 offset:22528
	s_nop 2
	v_mfma_f32_32x32x16_bf16 v[80:95], v[144:147], v[120:123], v[80:95]
	v_exp_f32_e32 v96, v96
	v_exp_f32_e32 v97, v97
	v_exp_f32_e32 v98, v98
	v_mfma_f32_32x32x16_bf16 v[80:95], v[152:155], v[124:127], v[80:95]
	v_exp_f32_e32 v99, v99
	v_exp_f32_e32 v100, v100
	v_exp_f32_e32 v101, v101
	v_exp_f32_e32 v102, v102
	v_exp_f32_e32 v103, v103
	v_cvt_pk_bf16_f32 v208, v96, v97
	v_cvt_pk_bf16_f32 v209, v98, v99
	v_cvt_pk_bf16_f32 v210, v100, v101
	v_cvt_pk_bf16_f32 v211, v102, v103
	v_exp_f32_e32 v104, v104
	v_exp_f32_e32 v105, v105
	s_waitcnt lgkmcnt(8)
	v_mfma_f32_32x32x16_bf16 v[48:63], v[224:227], v[208:211], v[48:63]
	v_exp_f32_e32 v106, v106
	v_exp_f32_e32 v107, v107
	v_exp_f32_e32 v108, v108
	v_mfma_f32_32x32x16_bf16 v[32:47], v[228:231], v[208:211], v[32:47]
	v_exp_f32_e32 v109, v109
	v_exp_f32_e32 v110, v110
	v_exp_f32_e32 v111, v111
	ds_read_b64_tr_b16 v[144:145], v174 offset:24576
	ds_read_b64_tr_b16 v[146:147], v175 offset:26624
	v_mfma_f32_32x32x16_bf16 v[16:31], v[232:235], v[208:211], v[16:31]
	v_cvt_pk_bf16_f32 v212, v104, v105
	v_cvt_pk_bf16_f32 v213, v106, v107
	v_cvt_pk_bf16_f32 v214, v108, v109
	v_cvt_pk_bf16_f32 v215, v110, v111
	v_add_f32_e32 v187, v96, v187
	v_add_f32_e32 v192, v97, v192
	ds_read_b64_tr_b16 v[148:149], v176 offset:24576
	ds_read_b64_tr_b16 v[150:151], v177 offset:26624
	v_mfma_f32_32x32x16_bf16 v[0:15], v[236:239], v[208:211], v[0:15]
	v_add_f32_e32 v193, v98, v193
	v_add_f32_e32 v194, v99, v194
	v_add_f32_e32 v187, v100, v187
	v_add_f32_e32 v192, v101, v192
	v_add_f32_e32 v193, v102, v193
	v_add_f32_e32 v194, v103, v194
	ds_read_b64_tr_b16 v[152:153], v178 offset:24576
	ds_read_b64_tr_b16 v[154:155], v179 offset:26624
	s_waitcnt lgkmcnt(6)
	v_mfma_f32_32x32x16_bf16 v[48:63], v[128:131], v[212:215], v[48:63]
	v_exp_f32_e32 v80, v80
	v_exp_f32_e32 v81, v81
	v_exp_f32_e32 v82, v82
	ds_read_b64_tr_b16 v[240:241], v183 offset:24576
	ds_read_b64_tr_b16 v[242:243], v184 offset:26624
	ds_read_b128 v[128:131], v188 offset:40960
	v_mfma_f32_32x32x16_bf16 v[32:47], v[132:135], v[212:215], v[32:47]
	v_exp_f32_e32 v83, v83
	v_exp_f32_e32 v84, v84
	v_exp_f32_e32 v85, v85
	ds_read_b64_tr_b16 v[196:197], v174 offset:28672
	ds_read_b64_tr_b16 v[198:199], v175 offset:30720
	ds_read_b128 v[132:135], v189 offset:32768
	v_mfma_f32_32x32x16_bf16 v[16:31], v[136:139], v[212:215], v[16:31]
	v_exp_f32_e32 v86, v86
	v_exp_f32_e32 v87, v87
	v_cvt_pk_bf16_f32 v216, v80, v81
	v_cvt_pk_bf16_f32 v217, v82, v83
	ds_read_b64_tr_b16 v[200:201], v176 offset:28672
	ds_read_b64_tr_b16 v[202:203], v177 offset:30720
	ds_read_b128 v[136:139], v189 offset:40960
	v_mfma_f32_32x32x16_bf16 v[0:15], v[140:143], v[212:215], v[0:15]
	v_cvt_pk_bf16_f32 v218, v84, v85
	v_cvt_pk_bf16_f32 v219, v86, v87
	v_add_f32_e32 v187, v104, v187
	v_add_f32_e32 v192, v105, v192
	v_add_f32_e32 v193, v106, v193
	v_add_f32_e32 v194, v107, v194
	s_waitcnt lgkmcnt(12)
	ds_read_b64_tr_b16 v[204:205], v178 offset:28672
	ds_read_b64_tr_b16 v[206:207], v179 offset:30720
	ds_read_b128 v[140:143], v190 offset:32768
	s_waitcnt lgkmcnt(10)
	v_mfma_f32_32x32x16_bf16 v[48:63], v[144:147], v[216:219], v[48:63]
	v_exp_f32_e32 v88, v88
	v_exp_f32_e32 v89, v89
	v_exp_f32_e32 v90, v90
	ds_read_b64_tr_b16 v[246:247], v183 offset:28672
	ds_read_b64_tr_b16 v[248:249], v184 offset:30720
	ds_read_b128 v[144:147], v190 offset:40960
	v_mfma_f32_32x32x16_bf16 v[32:47], v[148:151], v[216:219], v[32:47]
	v_exp_f32_e32 v91, v91
	v_exp_f32_e32 v92, v92
	v_exp_f32_e32 v93, v93
	ds_read_b128 v[148:151], v191 offset:32768
	v_mfma_f32_32x32x16_bf16 v[16:31], v[152:155], v[216:219], v[16:31]
	v_exp_f32_e32 v94, v94
	v_exp_f32_e32 v95, v95
	v_cvt_pk_bf16_f32 v220, v88, v89
	v_cvt_pk_bf16_f32 v221, v90, v91
	ds_read_b128 v[152:155], v191 offset:40960
	v_mfma_f32_32x32x16_bf16 v[0:15], v[240:243], v[216:219], v[0:15]
	v_cvt_pk_bf16_f32 v222, v92, v93
	v_cvt_pk_bf16_f32 v223, v94, v95
	v_add_f32_e32 v187, v80, v187
	v_add_f32_e32 v192, v81, v192
	v_add_f32_e32 v193, v82, v193
	v_add_f32_e32 v194, v83, v194
	s_waitcnt lgkmcnt(3)
	v_mfma_f32_32x32x16_bf16 v[48:63], v[196:199], v[220:223], v[48:63]
	v_add_f32_e32 v187, v108, v187
	v_add_f32_e32 v192, v109, v192
	v_add_f32_e32 v193, v110, v193
	v_add_f32_e32 v194, v111, v194
	v_add_f32_e32 v187, v84, v187
	v_add_f32_e32 v192, v85, v192
	ds_read_b128 v[80:83], v188 offset:32768
	ds_read_b64_tr_b16 v[224:225], v174 offset:32768
	ds_read_b64_tr_b16 v[226:227], v175 offset:34816
	v_mfma_f32_32x32x16_bf16 v[32:47], v[200:203], v[220:223], v[32:47]
	v_add_f32_e32 v193, v86, v193
	v_add_f32_e32 v194, v87, v194
	v_add_f32_e32 v187, v88, v187
	v_add_f32_e32 v192, v89, v192
	v_add_f32_e32 v193, v90, v193
	v_add_f32_e32 v194, v91, v194
	ds_read_b64_tr_b16 v[228:229], v176 offset:32768
	ds_read_b64_tr_b16 v[230:231], v177 offset:34816
	v_mfma_f32_32x32x16_bf16 v[16:31], v[204:207], v[220:223], v[16:31]
	v_add_f32_e32 v187, v92, v187
	v_add_f32_e32 v192, v93, v192
	v_add_f32_e32 v193, v94, v193
	v_add_f32_e32 v194, v95, v194
	ds_read_b64_tr_b16 v[232:233], v178 offset:32768
	ds_read_b64_tr_b16 v[234:235], v179 offset:34816
	v_mfma_f32_32x32x16_bf16 v[0:15], v[246:249], v[220:223], v[0:15]
	ds_read_b64_tr_b16 v[236:237], v183 offset:32768
	ds_read_b64_tr_b16 v[238:239], v184 offset:34816
	s_barrier
	v_mfma_f32_32x32x16_bf16 v[96:111], v[132:135], v[116:119], v[64:79]
	v_mfma_f32_32x32x16_bf16 v[96:111], v[140:143], v[120:123], v[96:111]
	s_waitcnt lgkmcnt(10)
	v_mfma_f32_32x32x16_bf16 v[96:111], v[148:151], v[124:127], v[96:111]
	ds_read_b64_tr_b16 v[132:133], v176 offset:36864
	ds_read_b64_tr_b16 v[134:135], v177 offset:38912
	s_waitcnt lgkmcnt(10)
	v_mfma_f32_32x32x16_bf16 v[96:111], v[80:83], v[112:115], v[96:111]
	ds_read_b64_tr_b16 v[140:141], v183 offset:36864
	ds_read_b64_tr_b16 v[142:143], v184 offset:38912
	v_mfma_f32_32x32x16_bf16 v[80:95], v[128:131], v[112:115], v[64:79]
	ds_read_b64_tr_b16 v[128:129], v174 offset:36864
	ds_read_b64_tr_b16 v[130:131], v175 offset:38912
	v_mfma_f32_32x32x16_bf16 v[80:95], v[136:139], v[116:119], v[80:95]
	ds_read_b64_tr_b16 v[136:137], v178 offset:36864
	s_waitcnt lgkmcnt(12)
	ds_read_b64_tr_b16 v[138:139], v179 offset:38912
	s_nop 2
	v_mfma_f32_32x32x16_bf16 v[80:95], v[144:147], v[120:123], v[80:95]
	v_exp_f32_e32 v96, v96
	v_exp_f32_e32 v97, v97
	v_exp_f32_e32 v98, v98
	v_mfma_f32_32x32x16_bf16 v[80:95], v[152:155], v[124:127], v[80:95]
	v_exp_f32_e32 v99, v99
	v_exp_f32_e32 v100, v100
	v_exp_f32_e32 v101, v101
	v_exp_f32_e32 v102, v102
	v_exp_f32_e32 v103, v103
	v_cvt_pk_bf16_f32 v208, v96, v97
	v_cvt_pk_bf16_f32 v209, v98, v99
	v_cvt_pk_bf16_f32 v210, v100, v101
	v_cvt_pk_bf16_f32 v211, v102, v103
	v_exp_f32_e32 v104, v104
	v_exp_f32_e32 v105, v105
	s_waitcnt lgkmcnt(8)
	v_mfma_f32_32x32x16_bf16 v[48:63], v[224:227], v[208:211], v[48:63]
	v_exp_f32_e32 v106, v106
	v_exp_f32_e32 v107, v107
	v_exp_f32_e32 v108, v108
	v_mfma_f32_32x32x16_bf16 v[32:47], v[228:231], v[208:211], v[32:47]
	v_exp_f32_e32 v109, v109
	v_exp_f32_e32 v110, v110
	v_exp_f32_e32 v111, v111
	ds_read_b64_tr_b16 v[144:145], v174 offset:40960
	ds_read_b64_tr_b16 v[146:147], v175 offset:43008
	v_mfma_f32_32x32x16_bf16 v[16:31], v[232:235], v[208:211], v[16:31]
	v_cvt_pk_bf16_f32 v212, v104, v105
	v_cvt_pk_bf16_f32 v213, v106, v107
	v_cvt_pk_bf16_f32 v214, v108, v109
	v_cvt_pk_bf16_f32 v215, v110, v111
	v_add_f32_e32 v187, v96, v187
	v_add_f32_e32 v192, v97, v192
	ds_read_b64_tr_b16 v[148:149], v176 offset:40960
	ds_read_b64_tr_b16 v[150:151], v177 offset:43008
	v_mfma_f32_32x32x16_bf16 v[0:15], v[236:239], v[208:211], v[0:15]
	v_add_f32_e32 v193, v98, v193
	v_add_f32_e32 v194, v99, v194
	v_add_f32_e32 v187, v100, v187
	v_add_f32_e32 v192, v101, v192
	v_add_f32_e32 v193, v102, v193
	v_add_f32_e32 v194, v103, v194
	ds_read_b64_tr_b16 v[152:153], v178 offset:40960
	ds_read_b64_tr_b16 v[154:155], v179 offset:43008
	s_waitcnt lgkmcnt(6)
	v_mfma_f32_32x32x16_bf16 v[48:63], v[128:131], v[212:215], v[48:63]
	v_exp_f32_e32 v80, v80
	v_exp_f32_e32 v81, v81
	v_exp_f32_e32 v82, v82
	ds_read_b64_tr_b16 v[240:241], v183 offset:40960
	ds_read_b64_tr_b16 v[242:243], v184 offset:43008
	ds_read_b128 v[128:131], v188 offset:57344
	v_mfma_f32_32x32x16_bf16 v[32:47], v[132:135], v[212:215], v[32:47]
	v_exp_f32_e32 v83, v83
	v_exp_f32_e32 v84, v84
	v_exp_f32_e32 v85, v85
	ds_read_b64_tr_b16 v[196:197], v174 offset:45056
	ds_read_b64_tr_b16 v[198:199], v175 offset:47104
	ds_read_b128 v[132:135], v189 offset:49152
	v_mfma_f32_32x32x16_bf16 v[16:31], v[136:139], v[212:215], v[16:31]
	v_exp_f32_e32 v86, v86
	v_exp_f32_e32 v87, v87
	v_cvt_pk_bf16_f32 v216, v80, v81
	v_cvt_pk_bf16_f32 v217, v82, v83
	ds_read_b64_tr_b16 v[200:201], v176 offset:45056
	ds_read_b64_tr_b16 v[202:203], v177 offset:47104
	ds_read_b128 v[136:139], v189 offset:57344
	v_mfma_f32_32x32x16_bf16 v[0:15], v[140:143], v[212:215], v[0:15]
	v_cvt_pk_bf16_f32 v218, v84, v85
	v_cvt_pk_bf16_f32 v219, v86, v87
	v_add_f32_e32 v187, v104, v187
	v_add_f32_e32 v192, v105, v192
	v_add_f32_e32 v193, v106, v193
	v_add_f32_e32 v194, v107, v194
	s_waitcnt lgkmcnt(12)
	ds_read_b64_tr_b16 v[204:205], v178 offset:45056
	ds_read_b64_tr_b16 v[206:207], v179 offset:47104
	ds_read_b128 v[140:143], v190 offset:49152
	s_waitcnt lgkmcnt(10)
	v_mfma_f32_32x32x16_bf16 v[48:63], v[144:147], v[216:219], v[48:63]
	v_exp_f32_e32 v88, v88
	v_exp_f32_e32 v89, v89
	v_exp_f32_e32 v90, v90
	ds_read_b64_tr_b16 v[246:247], v183 offset:45056
	ds_read_b64_tr_b16 v[248:249], v184 offset:47104
	ds_read_b128 v[144:147], v190 offset:57344
	v_mfma_f32_32x32x16_bf16 v[32:47], v[148:151], v[216:219], v[32:47]
	v_exp_f32_e32 v91, v91
	v_exp_f32_e32 v92, v92
	v_exp_f32_e32 v93, v93
	ds_read_b128 v[148:151], v191 offset:49152
	v_mfma_f32_32x32x16_bf16 v[16:31], v[152:155], v[216:219], v[16:31]
	v_exp_f32_e32 v94, v94
	v_exp_f32_e32 v95, v95
	v_cvt_pk_bf16_f32 v220, v88, v89
	v_cvt_pk_bf16_f32 v221, v90, v91
	ds_read_b128 v[152:155], v191 offset:57344
	v_mfma_f32_32x32x16_bf16 v[0:15], v[240:243], v[216:219], v[0:15]
	v_cvt_pk_bf16_f32 v222, v92, v93
	v_cvt_pk_bf16_f32 v223, v94, v95
	v_add_f32_e32 v187, v80, v187
	v_add_f32_e32 v192, v81, v192
	v_add_f32_e32 v193, v82, v193
	v_add_f32_e32 v194, v83, v194
	s_waitcnt lgkmcnt(3)
	v_mfma_f32_32x32x16_bf16 v[48:63], v[196:199], v[220:223], v[48:63]
	v_add_f32_e32 v187, v108, v187
	v_add_f32_e32 v192, v109, v192
	v_add_f32_e32 v193, v110, v193
	v_add_f32_e32 v194, v111, v194
	v_add_f32_e32 v187, v84, v187
	v_add_f32_e32 v192, v85, v192
	ds_read_b128 v[80:83], v188 offset:49152
	ds_read_b64_tr_b16 v[224:225], v174 offset:49152
	ds_read_b64_tr_b16 v[226:227], v175 offset:51200
	v_mfma_f32_32x32x16_bf16 v[32:47], v[200:203], v[220:223], v[32:47]
	v_add_f32_e32 v193, v86, v193
	v_add_f32_e32 v194, v87, v194
	v_add_f32_e32 v187, v88, v187
	v_add_f32_e32 v192, v89, v192
	v_add_f32_e32 v193, v90, v193
	v_add_f32_e32 v194, v91, v194
	ds_read_b64_tr_b16 v[228:229], v176 offset:49152
	ds_read_b64_tr_b16 v[230:231], v177 offset:51200
	v_mfma_f32_32x32x16_bf16 v[16:31], v[204:207], v[220:223], v[16:31]
	v_add_f32_e32 v187, v92, v187
	v_add_f32_e32 v192, v93, v192
	v_add_f32_e32 v193, v94, v193
	v_add_f32_e32 v194, v95, v194
	ds_read_b64_tr_b16 v[232:233], v178 offset:49152
	ds_read_b64_tr_b16 v[234:235], v179 offset:51200
	v_mfma_f32_32x32x16_bf16 v[0:15], v[246:249], v[220:223], v[0:15]
	ds_read_b64_tr_b16 v[236:237], v183 offset:49152
	ds_read_b64_tr_b16 v[238:239], v184 offset:51200
	s_barrier
; __device__ __forceinline__ void attn_unit(LAS unsigned char* L, bf16_t* QKV, size_t rowbase, int S, int h, int qb, float lam, const float* subln, unsigned* kmax) {
;     ...
;     for (int t = 0; t < NT; t += 4) { TILE(t, 0); TILE(t + 1, 1); TILE(t + 2, 2); TILE(t + 3, 3); }
	v_mfma_f32_32x32x16_bf16 v[96:111], v[132:135], v[116:119], v[64:79]
	v_mfma_f32_32x32x16_bf16 v[96:111], v[140:143], v[120:123], v[96:111]
	s_waitcnt lgkmcnt(10)
	v_mfma_f32_32x32x16_bf16 v[96:111], v[148:151], v[124:127], v[96:111]
	ds_read_b64_tr_b16 v[132:133], v176 offset:53248
	ds_read_b64_tr_b16 v[134:135], v177 offset:55296
	s_waitcnt lgkmcnt(10)
	v_mfma_f32_32x32x16_bf16 v[96:111], v[80:83], v[112:115], v[96:111]
	ds_read_b64_tr_b16 v[140:141], v183 offset:53248
	ds_read_b64_tr_b16 v[142:143], v184 offset:55296
	v_mfma_f32_32x32x16_bf16 v[80:95], v[128:131], v[112:115], v[64:79]
	ds_read_b64_tr_b16 v[128:129], v174 offset:53248
	ds_read_b64_tr_b16 v[130:131], v175 offset:55296
	v_mfma_f32_32x32x16_bf16 v[80:95], v[136:139], v[116:119], v[80:95]
	ds_read_b64_tr_b16 v[136:137], v178 offset:53248
	s_waitcnt lgkmcnt(12)
	ds_read_b64_tr_b16 v[138:139], v179 offset:55296
	s_nop 2
	v_mfma_f32_32x32x16_bf16 v[80:95], v[144:147], v[120:123], v[80:95]
	v_exp_f32_e32 v96, v96
	v_exp_f32_e32 v97, v97
	v_exp_f32_e32 v98, v98
	v_mfma_f32_32x32x16_bf16 v[80:95], v[152:155], v[124:127], v[80:95]
	v_exp_f32_e32 v99, v99
	v_exp_f32_e32 v100, v100
	v_exp_f32_e32 v101, v101
	v_exp_f32_e32 v102, v102
	v_exp_f32_e32 v103, v103
	v_cvt_pk_bf16_f32 v208, v96, v97
	v_cvt_pk_bf16_f32 v209, v98, v99
	v_cvt_pk_bf16_f32 v210, v100, v101
	v_cvt_pk_bf16_f32 v211, v102, v103
	v_exp_f32_e32 v104, v104
	v_exp_f32_e32 v105, v105
	s_waitcnt lgkmcnt(8)
	v_mfma_f32_32x32x16_bf16 v[48:63], v[224:227], v[208:211], v[48:63]
	v_exp_f32_e32 v106, v106
	v_exp_f32_e32 v107, v107
	v_exp_f32_e32 v108, v108
	v_mfma_f32_32x32x16_bf16 v[32:47], v[228:231], v[208:211], v[32:47]
	v_exp_f32_e32 v109, v109
	v_exp_f32_e32 v110, v110
	v_exp_f32_e32 v111, v111
	ds_read_b64_tr_b16 v[144:145], v174 offset:57344
	ds_read_b64_tr_b16 v[146:147], v175 offset:59392
	v_mfma_f32_32x32x16_bf16 v[16:31], v[232:235], v[208:211], v[16:31]
	v_cvt_pk_bf16_f32 v212, v104, v105
	v_cvt_pk_bf16_f32 v213, v106, v107
	v_cvt_pk_bf16_f32 v214, v108, v109
	v_cvt_pk_bf16_f32 v215, v110, v111
	v_add_f32_e32 v187, v96, v187
	v_add_f32_e32 v192, v97, v192
	ds_read_b64_tr_b16 v[148:149], v176 offset:57344
	ds_read_b64_tr_b16 v[150:151], v177 offset:59392
	v_mfma_f32_32x32x16_bf16 v[0:15], v[236:239], v[208:211], v[0:15]
	v_add_f32_e32 v193, v98, v193
	v_add_f32_e32 v194, v99, v194
	v_add_f32_e32 v187, v100, v187
	v_add_f32_e32 v192, v101, v192
	v_add_f32_e32 v193, v102, v193
	v_add_f32_e32 v194, v103, v194
	ds_read_b64_tr_b16 v[152:153], v178 offset:57344
	ds_read_b64_tr_b16 v[154:155], v179 offset:59392
	s_waitcnt lgkmcnt(6)
	v_mfma_f32_32x32x16_bf16 v[48:63], v[128:131], v[212:215], v[48:63]
	v_exp_f32_e32 v80, v80
	v_exp_f32_e32 v81, v81
	v_exp_f32_e32 v82, v82
	ds_read_b64_tr_b16 v[240:241], v183 offset:57344
	ds_read_b64_tr_b16 v[242:243], v184 offset:59392
	ds_read_b128 v[128:131], v188 offset:8192
	v_mfma_f32_32x32x16_bf16 v[32:47], v[132:135], v[212:215], v[32:47]
	v_exp_f32_e32 v83, v83
	v_exp_f32_e32 v84, v84
	v_exp_f32_e32 v85, v85
	ds_read_b64_tr_b16 v[196:197], v174 offset:61440
	ds_read_b64_tr_b16 v[198:199], v175 offset:63488
	ds_read_b128 v[132:135], v189
	v_mfma_f32_32x32x16_bf16 v[16:31], v[136:139], v[212:215], v[16:31]
	v_exp_f32_e32 v86, v86
	v_exp_f32_e32 v87, v87
	v_cvt_pk_bf16_f32 v216, v80, v81
	v_cvt_pk_bf16_f32 v217, v82, v83
	ds_read_b64_tr_b16 v[200:201], v176 offset:61440
	ds_read_b64_tr_b16 v[202:203], v177 offset:63488
	ds_read_b128 v[136:139], v189 offset:8192
	v_mfma_f32_32x32x16_bf16 v[0:15], v[140:143], v[212:215], v[0:15]
	v_cvt_pk_bf16_f32 v218, v84, v85
	v_cvt_pk_bf16_f32 v219, v86, v87
	v_add_f32_e32 v187, v104, v187
	v_add_f32_e32 v192, v105, v192
	v_add_f32_e32 v193, v106, v193
	v_add_f32_e32 v194, v107, v194
	s_waitcnt lgkmcnt(12)
	ds_read_b64_tr_b16 v[204:205], v178 offset:61440
	ds_read_b64_tr_b16 v[206:207], v179 offset:63488
	ds_read_b128 v[140:143], v190
	s_waitcnt lgkmcnt(10)
	v_mfma_f32_32x32x16_bf16 v[48:63], v[144:147], v[216:219], v[48:63]
	v_exp_f32_e32 v88, v88
	v_exp_f32_e32 v89, v89
	v_exp_f32_e32 v90, v90
	ds_read_b64_tr_b16 v[246:247], v183 offset:61440
	ds_read_b64_tr_b16 v[248:249], v184 offset:63488
	ds_read_b128 v[144:147], v190 offset:8192
	v_mfma_f32_32x32x16_bf16 v[32:47], v[148:151], v[216:219], v[32:47]
	v_exp_f32_e32 v91, v91
	v_exp_f32_e32 v92, v92
	v_exp_f32_e32 v93, v93
	ds_read_b128 v[148:151], v191
	v_mfma_f32_32x32x16_bf16 v[16:31], v[152:155], v[216:219], v[16:31]
	v_exp_f32_e32 v94, v94
	v_exp_f32_e32 v95, v95
	v_cvt_pk_bf16_f32 v220, v88, v89
	v_cvt_pk_bf16_f32 v221, v90, v91
	ds_read_b128 v[152:155], v191 offset:8192
	v_mfma_f32_32x32x16_bf16 v[0:15], v[240:243], v[216:219], v[0:15]
	v_cvt_pk_bf16_f32 v222, v92, v93
	v_cvt_pk_bf16_f32 v223, v94, v95
	v_add_f32_e32 v187, v80, v187
	v_add_f32_e32 v192, v81, v192
	v_add_f32_e32 v193, v82, v193
	v_add_f32_e32 v194, v83, v194
	s_waitcnt lgkmcnt(3)
	v_mfma_f32_32x32x16_bf16 v[48:63], v[196:199], v[220:223], v[48:63]
	v_add_f32_e32 v187, v108, v187
	v_add_f32_e32 v192, v109, v192
	v_add_f32_e32 v193, v110, v193
	v_add_f32_e32 v194, v111, v194
	v_add_f32_e32 v187, v84, v187
	v_add_f32_e32 v192, v85, v192
	ds_read_b128 v[80:83], v188
	ds_read_b64_tr_b16 v[224:225], v174
	ds_read_b64_tr_b16 v[226:227], v175 offset:2048
	v_mfma_f32_32x32x16_bf16 v[32:47], v[200:203], v[220:223], v[32:47]
	v_add_f32_e32 v193, v86, v193
	v_add_f32_e32 v194, v87, v194
	v_add_f32_e32 v187, v88, v187
	v_add_f32_e32 v192, v89, v192
	v_add_f32_e32 v193, v90, v193
	v_add_f32_e32 v194, v91, v194
	ds_read_b64_tr_b16 v[228:229], v176
	ds_read_b64_tr_b16 v[230:231], v177 offset:2048
	v_mfma_f32_32x32x16_bf16 v[16:31], v[204:207], v[220:223], v[16:31]
	v_add_f32_e32 v187, v92, v187
	v_add_f32_e32 v192, v93, v192
	v_add_f32_e32 v193, v94, v193
	v_add_f32_e32 v194, v95, v194
	ds_read_b64_tr_b16 v[232:233], v178
	ds_read_b64_tr_b16 v[234:235], v179 offset:2048
	v_mfma_f32_32x32x16_bf16 v[0:15], v[246:249], v[220:223], v[0:15]
	ds_read_b64_tr_b16 v[236:237], v183
	ds_read_b64_tr_b16 v[238:239], v184 offset:2048
	s_add_i32 s68, s68, 4
	s_cmp_ge_u32 s69, s42
	s_barrier
	s_cbranch_scc0 .LBB0_927
	s_branch .Lattn_join
